# all but 160 plain-copy units moved into gate/up epilogues (6 rounds x two 12KB row groups per wave); attention phase keeps only the groups workgroups 216-255 cannot reach
# speedup vs baseline: 1.0348x; 1.0111x over previous
.LBB0_1209:
	v_readlane_b32 s10, v240, 0
	s_add_i32 s12, s8, s10
	s_lshl_b32 s8, s95, 8
	s_add_i32 s8, s8, s15
	s_ashr_i32 s9, s8, 7
	v_readlane_b32 s11, v240, 1
	s_mul_hi_i32 s10, s9, 0x55555556
	s_lshr_b32 s11, s10, 31
	s_add_i32 s10, s10, s11
	s_mul_i32 s11, s14, 3
	s_add_i32 s11, s10, s11
	s_mul_i32 s10, s10, 3
	s_mul_i32 s11, s11, 3
	s_sub_i32 s10, s9, s10
	s_add_i32 s11, s11, s10
	s_mul_hi_i32 s10, s8, 0x30c30c31
	s_lshr_b32 s16, s10, 31
	s_ashr_i32 s10, s10, 4
	s_add_i32 s10, s10, s16
	s_lshl_b32 s16, s10, 3
	s_or_b32 s16, s16, s14
	s_mulk_i32 s10, 0x54
	s_mulk_i32 s16, 0x54
	s_sub_i32 s10, s8, s10
	s_add_i32 s13, s12, 0x2a00
	s_add_i32 s96, s12, 0xffffd600
	s_add_i32 s16, s16, s10
	s_cmp_lt_u32 s9, 12
	s_cselect_b32 s10, s19, s2
	s_add_i32 s10, s10, s9
	s_cmp_lt_i32 s9, 9
	s_cselect_b32 s9, s11, s10
	s_lshl_b32 s9, s9, 7
	s_add_i32 s17, s9, s35
	s_cmpk_lt_i32 s8, 0x540
	s_cselect_b32 s10, s16, -1
	s_and_b64 s[8:9], s[58:59], exec
	s_cselect_b32 s16, s12, s10
	s_cmpk_gt_i32 s12, 0x29ff
	s_cselect_b64 s[8:9], -1, 0
	s_and_b64 s[10:11], s[8:9], exec
	s_cselect_b32 s97, -1, s16
	s_or_b64 s[8:9], s[8:9], s[58:59]
	s_cmpk_lt_u32 s96, 0xa0
	s_cselect_b64 s[10:11], -1, 0
	s_and_b64 s[74:75], s[8:9], s[10:11]
	s_and_b64 s[8:9], s[58:59], exec
	s_cselect_b32 s8, s13, s17
	s_cmpk_lt_i32 s12, 0x3800
	s_mov_b32 s40, s82
	s_cselect_b32 s52, s8, -1
	s_mov_b64 s[76:77], -1
	s_mov_b32 s10, s57
	s_branch .LBB0_1212

.LBB0_1216:
	s_and_b64 s[10:11], s[8:9], exec
	s_cselect_b32 s53, s97, s52
	s_cmp_lt_i32 s53, 0
	s_mov_b64 s[10:11], -1
	s_cbranch_scc0 .LBB0_1220
	s_and_b64 s[8:9], s[8:9], s[74:75]
	s_andn2_b64 vcc, exec, s[8:9]
	s_cbranch_vccnz .LBB0_1219
	s_and_b64 s[8:9], s[8:9], exec
	s_cselect_b32 s12, s96, -1
	s_mul_i32 s98, s12, 0xcd
	s_lshr_b32 s98, s98, 13
	s_mul_i32 s99, s98, 40
	s_sub_u32 s99, s12, s99
	s_cmp_ge_u32 s98, 2
	s_cselect_b32 s100, 10, 0
	s_add_u32 s98, s98, s100
	s_add_u32 s98, s98, 10
	s_lshl_b32 s98, s98, 8
	s_add_u32 s99, s99, 0x58
	s_lshl_b32 s99, s99, 1
	s_or_b32 s12, s98, s99
	s_or_b32 s12, s12, 1
	s_and_b32 s10, s12, 1
	s_lshl_b32 s8, s10, 3
	s_load_dwordx2 s[8:9], s[0:1], s8 offset:0x20
	s_lshl_b32 s11, s12, 10
	s_and_b32 s11, s11, 0x3f800
	s_mulk_i32 s11, 0x600
	v_mov_b32_e32 v133, v121
	s_waitcnt lgkmcnt(0)
	s_add_u32 s8, s8, s11
	s_addc_u32 s9, s9, 0
	s_cmp_eq_u32 s10, 0
	s_mov_b32 s10, 0x6e80000
	s_cselect_b32 s10, s10, 0x1ee80000
	s_add_u32 s10, s28, s10
	s_addc_u32 s13, s29, 0
	s_add_u32 s10, s10, s11
	s_addc_u32 s11, s13, 0
	v_lshl_add_u64 v[2:3], s[8:9], 0, v[132:133]
	s_lshr_b32 s8, s12, 2
	s_and_b32 s9, s8, 0x1fffffc0
	v_lshl_add_u64 v[0:1], s[10:11], 0, v[132:133]
	s_or_b32 s10, s9, 8
	v_mad_u64_u32 v[20:21], s[10:11], s10, v172, v[2:3]
	global_load_dwordx4 v[4:7], v[20:21], off nt
	global_load_dwordx4 v[8:11], v[20:21], off offset:1024 nt
	global_load_dwordx4 v[12:15], v[20:21], off offset:2048 nt
	global_load_dwordx4 v[16:19], v[20:21], off offset:3072 nt
	v_add_co_u32_e32 v32, vcc, s87, v20
	s_or_b32 s10, s9, 24
	s_nop 0
	v_addc_co_u32_e32 v33, vcc, 0, v21, vcc
	s_waitcnt vmcnt(7)
	v_add_co_u32_e32 v48, vcc, s88, v20
	v_mad_u64_u32 v[68:69], s[10:11], s10, v172, v[2:3]
	s_nop 0
	v_addc_co_u32_e32 v49, vcc, 0, v21, vcc
	global_load_dwordx4 v[20:23], v[48:49], off offset:-4096 nt
	global_load_dwordx4 v[24:27], v[32:33], off offset:1024 nt
	global_load_dwordx4 v[28:31], v[32:33], off offset:2048 nt
	s_nop 0
	global_load_dwordx4 v[32:35], v[32:33], off offset:3072 nt
	s_nop 0
	global_load_dwordx4 v[36:39], v[48:49], off nt
	global_load_dwordx4 v[40:43], v[48:49], off offset:1024 nt
	global_load_dwordx4 v[44:47], v[48:49], off offset:2048 nt
	s_nop 0
	global_load_dwordx4 v[48:51], v[48:49], off offset:3072 nt
	s_waitcnt vmcnt(13)
	v_add_co_u32_e32 v80, vcc, s87, v68
	global_load_dwordx4 v[52:55], v[68:69], off nt
	global_load_dwordx4 v[56:59], v[68:69], off offset:1024 nt
	global_load_dwordx4 v[60:63], v[68:69], off offset:2048 nt
	global_load_dwordx4 v[64:67], v[68:69], off offset:3072 nt
	v_addc_co_u32_e32 v81, vcc, 0, v69, vcc
	v_add_co_u32_e32 v96, vcc, s88, v68
	v_mad_u64_u32 v[100:101], s[10:11], s9, v172, v[0:1]
	s_nop 0
	v_addc_co_u32_e32 v97, vcc, 0, v69, vcc
	global_load_dwordx4 v[68:71], v[96:97], off offset:-4096 nt
	global_load_dwordx4 v[72:75], v[80:81], off offset:1024 nt
	global_load_dwordx4 v[76:79], v[80:81], off offset:2048 nt
	s_nop 0
	global_load_dwordx4 v[80:83], v[80:81], off offset:3072 nt
	s_nop 0
	global_load_dwordx4 v[84:87], v[96:97], off nt
	global_load_dwordx4 v[88:91], v[96:97], off offset:1024 nt
	global_load_dwordx4 v[92:95], v[96:97], off offset:2048 nt
	s_nop 0
	global_load_dwordx4 v[96:99], v[96:97], off offset:3072 nt
	s_or_b32 s12, s9, 16
	s_and_b32 s8, s8, 0x3ffffff0
	s_waitcnt vmcnt(23)
	global_store_dwordx4 v[100:101], v[4:7], off nt
	s_waitcnt vmcnt(23)
	global_store_dwordx4 v[100:101], v[8:11], off offset:1024 nt
	s_waitcnt vmcnt(23)
	global_store_dwordx4 v[100:101], v[12:15], off offset:2048 nt
	s_waitcnt vmcnt(23)
	global_store_dwordx4 v[100:101], v[16:19], off offset:3072 nt
	v_add_co_u32_e32 v4, vcc, s87, v100
	s_nop 1
	v_addc_co_u32_e32 v5, vcc, 0, v101, vcc
	v_add_co_u32_e32 v6, vcc, s88, v100
	s_nop 1
	v_addc_co_u32_e32 v7, vcc, 0, v101, vcc
	s_waitcnt vmcnt(23)
	global_store_dwordx4 v[6:7], v[20:23], off offset:-4096 nt
	s_waitcnt vmcnt(23)
	global_store_dwordx4 v[4:5], v[24:27], off offset:1024 nt
	s_waitcnt vmcnt(23)
	global_store_dwordx4 v[4:5], v[28:31], off offset:2048 nt
	s_waitcnt vmcnt(23)
	global_store_dwordx4 v[4:5], v[32:35], off offset:3072 nt
	s_waitcnt vmcnt(23)
	global_store_dwordx4 v[6:7], v[36:39], off nt
	s_waitcnt vmcnt(23)
	global_store_dwordx4 v[6:7], v[40:43], off offset:1024 nt
	s_waitcnt vmcnt(23)
	global_store_dwordx4 v[6:7], v[44:47], off offset:2048 nt
	s_waitcnt vmcnt(23)
	global_store_dwordx4 v[6:7], v[48:51], off offset:3072 nt
	v_mad_u64_u32 v[4:5], s[10:11], s12, v172, v[0:1]
	v_add_co_u32_e32 v6, vcc, s87, v4
	s_waitcnt vmcnt(23)
	global_store_dwordx4 v[4:5], v[52:55], off nt
	s_waitcnt vmcnt(23)
	global_store_dwordx4 v[4:5], v[56:59], off offset:1024 nt
	s_waitcnt vmcnt(23)
	global_store_dwordx4 v[4:5], v[60:63], off offset:2048 nt
	s_waitcnt vmcnt(23)
	global_store_dwordx4 v[4:5], v[64:67], off offset:3072 nt
	v_addc_co_u32_e32 v7, vcc, 0, v5, vcc
	v_add_co_u32_e32 v4, vcc, s88, v4
	s_or_b32 s12, s9, 32
	s_nop 0
	v_addc_co_u32_e32 v5, vcc, 0, v5, vcc
	s_or_b32 s9, s9, 40
	s_waitcnt vmcnt(23)
	global_store_dwordx4 v[4:5], v[68:71], off offset:-4096 nt
	s_waitcnt vmcnt(23)
	global_store_dwordx4 v[6:7], v[72:75], off offset:1024 nt
	s_waitcnt vmcnt(23)
	global_store_dwordx4 v[6:7], v[76:79], off offset:2048 nt
	s_waitcnt vmcnt(23)
	global_store_dwordx4 v[6:7], v[80:83], off offset:3072 nt
	s_waitcnt vmcnt(23)
	global_store_dwordx4 v[4:5], v[84:87], off nt
	s_waitcnt vmcnt(23)
	global_store_dwordx4 v[4:5], v[88:91], off offset:1024 nt
	s_waitcnt vmcnt(23)
	global_store_dwordx4 v[4:5], v[92:95], off offset:2048 nt
	s_waitcnt vmcnt(23)
	global_store_dwordx4 v[4:5], v[96:99], off offset:3072 nt
	v_mad_u64_u32 v[20:21], s[10:11], s9, v172, v[2:3]
	global_load_dwordx4 v[4:7], v[20:21], off nt
	global_load_dwordx4 v[8:11], v[20:21], off offset:1024 nt
	global_load_dwordx4 v[12:15], v[20:21], off offset:2048 nt
	global_load_dwordx4 v[16:19], v[20:21], off offset:3072 nt
	v_add_co_u32_e32 v32, vcc, s87, v20
	s_or_b32 s10, s8, 48
	s_nop 0
	v_addc_co_u32_e32 v33, vcc, 0, v21, vcc
	v_add_co_u32_e32 v48, vcc, s88, v20
	s_or_b32 s8, s8, 56
	s_nop 0
	v_addc_co_u32_e32 v49, vcc, 0, v21, vcc
	v_mad_u64_u32 v[2:3], s[8:9], s8, v172, v[2:3]
	global_load_dwordx4 v[20:23], v[48:49], off offset:-4096 nt
	global_load_dwordx4 v[24:27], v[32:33], off offset:1024 nt
	global_load_dwordx4 v[28:31], v[32:33], off offset:2048 nt
	s_nop 0
	global_load_dwordx4 v[32:35], v[32:33], off offset:3072 nt
	s_nop 0
	global_load_dwordx4 v[36:39], v[48:49], off nt
	global_load_dwordx4 v[40:43], v[48:49], off offset:1024 nt
	global_load_dwordx4 v[44:47], v[48:49], off offset:2048 nt
	s_nop 0
	global_load_dwordx4 v[48:51], v[48:49], off offset:3072 nt
	v_add_co_u32_e32 v80, vcc, s87, v2
	global_load_dwordx4 v[52:55], v[2:3], off nt
	global_load_dwordx4 v[56:59], v[2:3], off offset:1024 nt
	global_load_dwordx4 v[60:63], v[2:3], off offset:2048 nt
	global_load_dwordx4 v[64:67], v[2:3], off offset:3072 nt
	v_addc_co_u32_e32 v81, vcc, 0, v3, vcc
	v_add_co_u32_e32 v2, vcc, s88, v2
	s_nop 1
	v_addc_co_u32_e32 v3, vcc, 0, v3, vcc
	global_load_dwordx4 v[68:71], v[2:3], off offset:-4096 nt
	global_load_dwordx4 v[72:75], v[80:81], off offset:1024 nt
	global_load_dwordx4 v[76:79], v[80:81], off offset:2048 nt
	s_nop 0
	global_load_dwordx4 v[80:83], v[80:81], off offset:3072 nt
	s_nop 0
	global_load_dwordx4 v[84:87], v[2:3], off nt
	global_load_dwordx4 v[88:91], v[2:3], off offset:1024 nt
	global_load_dwordx4 v[92:95], v[2:3], off offset:2048 nt
	global_load_dwordx4 v[96:99], v[2:3], off offset:3072 nt
	v_mad_u64_u32 v[2:3], s[8:9], s12, v172, v[0:1]
	v_mad_u64_u32 v[0:1], s[8:9], s10, v172, v[0:1]
	s_waitcnt vmcnt(23)
	global_store_dwordx4 v[2:3], v[4:7], off nt
	s_waitcnt vmcnt(23)
	global_store_dwordx4 v[2:3], v[8:11], off offset:1024 nt
	s_waitcnt vmcnt(23)
	global_store_dwordx4 v[2:3], v[12:15], off offset:2048 nt
	s_waitcnt vmcnt(23)
	global_store_dwordx4 v[2:3], v[16:19], off offset:3072 nt
	v_add_co_u32_e32 v4, vcc, s87, v2
	s_nop 1
	v_addc_co_u32_e32 v5, vcc, 0, v3, vcc
	v_add_co_u32_e32 v2, vcc, 0x2000, v2
	s_waitcnt vmcnt(23)
	global_store_dwordx4 v[4:5], v[20:23], off nt
	s_waitcnt vmcnt(23)
	global_store_dwordx4 v[4:5], v[24:27], off offset:1024 nt
	s_waitcnt vmcnt(23)
	global_store_dwordx4 v[4:5], v[28:31], off offset:2048 nt
	s_waitcnt vmcnt(23)
	global_store_dwordx4 v[4:5], v[32:35], off offset:3072 nt
	v_addc_co_u32_e32 v3, vcc, 0, v3, vcc
	s_waitcnt vmcnt(23)
	global_store_dwordx4 v[2:3], v[36:39], off nt
	s_waitcnt vmcnt(23)
	global_store_dwordx4 v[2:3], v[40:43], off offset:1024 nt
	s_waitcnt vmcnt(23)
	global_store_dwordx4 v[2:3], v[44:47], off offset:2048 nt
	s_waitcnt vmcnt(23)
	global_store_dwordx4 v[2:3], v[48:51], off offset:3072 nt
	v_add_co_u32_e32 v2, vcc, 0x1000, v0
	s_waitcnt vmcnt(23)
	global_store_dwordx4 v[0:1], v[52:55], off nt
	s_waitcnt vmcnt(23)
	global_store_dwordx4 v[0:1], v[56:59], off offset:1024 nt
	s_waitcnt vmcnt(23)
	global_store_dwordx4 v[0:1], v[60:63], off offset:2048 nt
	s_waitcnt vmcnt(23)
	global_store_dwordx4 v[0:1], v[64:67], off offset:3072 nt
	v_addc_co_u32_e32 v3, vcc, 0, v1, vcc
	v_add_co_u32_e32 v0, vcc, 0x2000, v0
	s_waitcnt vmcnt(23)
	global_store_dwordx4 v[2:3], v[68:71], off nt
	s_waitcnt vmcnt(23)
	global_store_dwordx4 v[2:3], v[72:75], off offset:1024 nt
	s_waitcnt vmcnt(23)
	global_store_dwordx4 v[2:3], v[76:79], off offset:2048 nt
	s_waitcnt vmcnt(23)
	global_store_dwordx4 v[2:3], v[80:83], off offset:3072 nt
	v_addc_co_u32_e32 v1, vcc, 0, v1, vcc
	s_waitcnt vmcnt(23)
	global_store_dwordx4 v[0:1], v[84:87], off nt
	s_waitcnt vmcnt(23)
	global_store_dwordx4 v[0:1], v[88:91], off offset:1024 nt
	s_waitcnt vmcnt(23)
	global_store_dwordx4 v[0:1], v[92:95], off offset:2048 nt
	s_waitcnt vmcnt(23)
	global_store_dwordx4 v[0:1], v[96:99], off offset:3072 nt

.LBB0_1661:
	s_add_u32 vcc_lo, s5, 0x120000
	buffer_load_dwordx4 v[166:169], v246, s[96:99], s5 offen nt
	buffer_load_dwordx4 v[170:173], v246, s[96:99], s5 offen offset:1024 nt
	buffer_load_dwordx4 v[174:177], v246, s[96:99], s5 offen offset:2048 nt
	buffer_load_dwordx4 v[178:181], v246, s[96:99], s5 offen offset:3072 nt
	buffer_load_dwordx4 v[182:185], v238, s[96:99], s5 offen nt
	buffer_load_dwordx4 v[186:189], v238, s[96:99], s5 offen offset:1024 nt
	buffer_load_dwordx4 v[190:193], v238, s[96:99], s5 offen offset:2048 nt
	buffer_load_dwordx4 v[194:197], v238, s[96:99], s5 offen offset:3072 nt
	buffer_load_dwordx4 v[198:201], v239, s[96:99], s5 offen nt
	buffer_load_dwordx4 v[202:205], v239, s[96:99], s5 offen offset:1024 nt
	buffer_load_dwordx4 v[206:209], v239, s[96:99], s5 offen offset:2048 nt
	buffer_load_dwordx4 v[210:213], v239, s[96:99], s5 offen offset:3072 nt
	buffer_load_dwordx4 v[158:161], v246, s[96:99], vcc_lo offen nt
	buffer_load_dwordx4 v[214:217], v246, s[96:99], vcc_lo offen offset:1024 nt
	buffer_load_dwordx4 v[218:221], v246, s[96:99], vcc_lo offen offset:2048 nt
	buffer_load_dwordx4 v[222:225], v246, s[96:99], vcc_lo offen offset:3072 nt
	buffer_load_dwordx4 v[226:229], v238, s[96:99], vcc_lo offen nt
	buffer_load_dwordx4 v[230:233], v238, s[96:99], vcc_lo offen offset:1024 nt
	buffer_load_dwordx4 v[234:237], v238, s[96:99], vcc_lo offen offset:2048 nt
	buffer_load_dwordx4 v[242:245], v238, s[96:99], vcc_lo offen offset:3072 nt
	v_mul_f32_e32 v153, 0xbfb8aa3b, v124
	v_exp_f32_e32 v153, v153
	v_mul_f32_e32 v154, 0xbfb8aa3b, v125
	v_exp_f32_e32 v155, v154
	s_lshl_b32 s48, s2, 7
	v_add_f32_e32 v153, 1.0, v153
	v_rcp_f32_e32 v154, v153
	v_add_f32_e32 v153, 1.0, v155
	v_mul_f32_e32 v155, 0xbfb8aa3b, v126
	v_exp_f32_e32 v156, v155
	v_mul_f32_e32 v155, 0xbfb8aa3b, v127
	v_exp_f32_e32 v157, v155
	v_rcp_f32_e32 v155, v153
	v_add_f32_e32 v153, 1.0, v156
	v_rcp_f32_e32 v156, v153
	v_add_f32_e32 v153, 1.0, v157
	v_rcp_f32_e32 v157, v153
	v_pk_mul_f32 v[124:125], v[124:125], v[154:155]
	v_mul_f32_e32 v153, 0xbfb8aa3b, v118
	v_pk_mul_f32 v[120:121], v[120:121], v[124:125]
	v_pk_mul_f32 v[124:125], v[126:127], v[156:157]
	v_mul_f32_e32 v126, 0xbfb8aa3b, v116
	v_mul_f32_e32 v127, 0xbfb8aa3b, v117
	v_exp_f32_e32 v126, v126
	v_exp_f32_e32 v127, v127
	v_exp_f32_e32 v153, v153
	v_mul_f32_e32 v154, 0xbfb8aa3b, v119
	v_exp_f32_e32 v155, v154
	v_add_f32_e32 v126, 1.0, v126
	v_add_f32_e32 v127, 1.0, v127
	v_add_f32_e32 v153, 1.0, v153
	v_rcp_f32_e32 v126, v126
	v_rcp_f32_e32 v127, v127
	v_rcp_f32_e32 v154, v153
	v_add_f32_e32 v153, 1.0, v155
	v_rcp_f32_e32 v155, v153
	v_pk_mul_f32 v[116:117], v[116:117], v[126:127]
	v_lshl_add_u32 v152, s56, 8, v129
	v_pk_mul_f32 v[112:113], v[112:113], v[116:117]
	v_pk_mul_f32 v[116:117], v[118:119], v[154:155]
	s_ashr_i32 s49, s48, 31
	v_pk_mul_f32 v[114:115], v[114:115], v[116:117]
	v_pk_mul_f32 v[122:123], v[122:123], v[124:125]
	v_cvt_pk_bf16_f32 v124, v120, v121
	v_mov_b64_e32 v[120:121], s[8:9]
	v_cvt_pk_bf16_f32 v112, v112, v113
	v_cvt_pk_bf16_f32 v113, v114, v115
	v_mul_f32_e32 v114, 0xbfb8aa3b, v108
	v_mul_f32_e32 v115, 0xbfb8aa3b, v109
	v_cvt_pk_bf16_f32 v125, v122, v123
	v_mad_i64_i32 v[122:123], s[50:51], v152, s66, v[120:121]
	s_lshl_b64 s[56:57], s[48:49], 1
	v_exp_f32_e32 v114, v114
	v_exp_f32_e32 v115, v115
	v_lshl_add_u64 v[122:123], v[122:123], 0, s[56:57]
	v_lshl_add_u64 v[122:123], v[122:123], 0, s[10:11]
	v_lshl_add_u64 v[122:123], v[122:123], 0, v[138:139]
	global_store_dwordx2 v[122:123], v[112:113], off offset:128
	v_add_f32_e32 v112, 1.0, v114
	v_add_f32_e32 v113, 1.0, v115
	v_mul_f32_e32 v114, 0xbfb8aa3b, v110
	v_mul_f32_e32 v115, 0xbfb8aa3b, v111
	v_exp_f32_e32 v114, v114
	v_exp_f32_e32 v115, v115
	v_rcp_f32_e32 v112, v112
	v_rcp_f32_e32 v113, v113
	v_add_f32_e32 v114, 1.0, v114
	v_add_f32_e32 v115, 1.0, v115
	v_rcp_f32_e32 v114, v114
	v_rcp_f32_e32 v115, v115
	v_pk_mul_f32 v[108:109], v[108:109], v[112:113]
	v_or_b32_e32 v116, 16, v152
	v_pk_mul_f32 v[104:105], v[104:105], v[108:109]
	v_pk_mul_f32 v[108:109], v[110:111], v[114:115]
	buffer_load_dwordx4 v[112:115], v239, s[96:99], vcc_lo offen nt
	v_mul_f32_e32 v110, 0xbfb8aa3b, v102
	v_pk_mul_f32 v[106:107], v[106:107], v[108:109]
	v_mul_f32_e32 v108, 0xbfb8aa3b, v100
	v_mul_f32_e32 v109, 0xbfb8aa3b, v101
	v_exp_f32_e32 v108, v108
	v_exp_f32_e32 v109, v109
	v_mul_f32_e32 v111, 0xbfb8aa3b, v103
	v_exp_f32_e32 v110, v110
	v_exp_f32_e32 v111, v111
	v_add_f32_e32 v108, 1.0, v108
	v_add_f32_e32 v109, 1.0, v109
	v_rcp_f32_e32 v108, v108
	v_rcp_f32_e32 v109, v109
	v_add_f32_e32 v110, 1.0, v110
	v_add_f32_e32 v111, 1.0, v111
	v_rcp_f32_e32 v110, v110
	v_rcp_f32_e32 v111, v111
	v_pk_mul_f32 v[100:101], v[100:101], v[108:109]
	v_cvt_pk_bf16_f32 v104, v104, v105
	v_pk_mul_f32 v[96:97], v[96:97], v[100:101]
	v_pk_mul_f32 v[100:101], v[102:103], v[110:111]
	buffer_load_dwordx4 v[108:111], v239, s[96:99], vcc_lo offen offset:1024 nt
	v_cvt_pk_bf16_f32 v96, v96, v97
	v_pk_mul_f32 v[98:99], v[98:99], v[100:101]
	v_cvt_pk_bf16_f32 v105, v106, v107
	v_cvt_pk_bf16_f32 v97, v98, v99
	v_mul_f32_e32 v98, 0xbfb8aa3b, v92
	v_mul_f32_e32 v99, 0xbfb8aa3b, v93
	v_mad_i64_i32 v[106:107], s[48:49], v116, s66, v[120:121]
	buffer_load_dwordx4 v[116:119], v239, s[96:99], vcc_lo offen offset:2048 nt
	v_exp_f32_e32 v98, v98
	v_exp_f32_e32 v99, v99
	v_lshl_add_u64 v[106:107], v[106:107], 0, s[56:57]
	v_lshl_add_u64 v[106:107], v[106:107], 0, s[10:11]
	v_lshl_add_u64 v[106:107], v[106:107], 0, v[138:139]
	global_store_dwordx2 v[106:107], v[96:97], off offset:128
	v_add_f32_e32 v96, 1.0, v98
	v_add_f32_e32 v97, 1.0, v99
	v_mul_f32_e32 v98, 0xbfb8aa3b, v94
	v_mul_f32_e32 v99, 0xbfb8aa3b, v95
	v_exp_f32_e32 v98, v98
	v_exp_f32_e32 v99, v99
	v_rcp_f32_e32 v96, v96
	v_rcp_f32_e32 v97, v97
	v_add_f32_e32 v98, 1.0, v98
	v_add_f32_e32 v99, 1.0, v99
	v_rcp_f32_e32 v98, v98
	v_rcp_f32_e32 v99, v99
	v_pk_mul_f32 v[92:93], v[92:93], v[96:97]
	v_or_b32_e32 v100, 32, v152
	v_pk_mul_f32 v[88:89], v[88:89], v[92:93]
	v_pk_mul_f32 v[92:93], v[94:95], v[98:99]
	buffer_load_dwordx4 v[96:99], v239, s[96:99], vcc_lo offen offset:3072 nt
	v_mul_f32_e32 v94, 0xbfb8aa3b, v86
	v_pk_mul_f32 v[90:91], v[90:91], v[92:93]
	v_mul_f32_e32 v92, 0xbfb8aa3b, v84
	v_mul_f32_e32 v93, 0xbfb8aa3b, v85
	v_exp_f32_e32 v92, v92
	v_exp_f32_e32 v93, v93
	v_mul_f32_e32 v95, 0xbfb8aa3b, v87
	v_exp_f32_e32 v94, v94
	v_exp_f32_e32 v95, v95
	v_add_f32_e32 v92, 1.0, v92
	v_add_f32_e32 v93, 1.0, v93
	v_rcp_f32_e32 v92, v92
	v_rcp_f32_e32 v93, v93
	v_add_f32_e32 v94, 1.0, v94
	v_add_f32_e32 v95, 1.0, v95
	v_rcp_f32_e32 v94, v94
	v_rcp_f32_e32 v95, v95
	v_pk_mul_f32 v[84:85], v[84:85], v[92:93]
	v_cvt_pk_bf16_f32 v88, v88, v89
	v_pk_mul_f32 v[80:81], v[80:81], v[84:85]
	v_pk_mul_f32 v[84:85], v[86:87], v[94:95]
	v_cvt_pk_bf16_f32 v80, v80, v81
	v_pk_mul_f32 v[82:83], v[82:83], v[84:85]
	v_cvt_pk_bf16_f32 v89, v90, v91
	v_cvt_pk_bf16_f32 v81, v82, v83
	v_mul_f32_e32 v82, 0xbfb8aa3b, v76
	v_mul_f32_e32 v83, 0xbfb8aa3b, v77
	v_mad_i64_i32 v[90:91], s[48:49], v100, s66, v[120:121]
	v_exp_f32_e32 v82, v82
	v_exp_f32_e32 v83, v83
	v_lshl_add_u64 v[90:91], v[90:91], 0, s[56:57]
	v_lshl_add_u64 v[90:91], v[90:91], 0, s[10:11]
	v_lshl_add_u64 v[90:91], v[90:91], 0, v[138:139]
	global_store_dwordx2 v[90:91], v[80:81], off offset:128
	v_add_f32_e32 v80, 1.0, v82
	v_add_f32_e32 v81, 1.0, v83
	v_mul_f32_e32 v82, 0xbfb8aa3b, v78
	v_mul_f32_e32 v83, 0xbfb8aa3b, v79
	v_exp_f32_e32 v82, v82
	v_exp_f32_e32 v83, v83
	v_rcp_f32_e32 v80, v80
	v_rcp_f32_e32 v81, v81
	v_add_f32_e32 v82, 1.0, v82
	v_add_f32_e32 v83, 1.0, v83
	v_rcp_f32_e32 v82, v82
	v_rcp_f32_e32 v83, v83
	v_pk_mul_f32 v[76:77], v[76:77], v[80:81]
	v_or_b32_e32 v84, 48, v152
	v_pk_mul_f32 v[72:73], v[72:73], v[76:77]
	v_pk_mul_f32 v[76:77], v[78:79], v[82:83]
	v_mul_f32_e32 v78, 0xbfb8aa3b, v70
	v_pk_mul_f32 v[74:75], v[74:75], v[76:77]
	v_mul_f32_e32 v76, 0xbfb8aa3b, v68
	v_mul_f32_e32 v77, 0xbfb8aa3b, v69
	v_exp_f32_e32 v76, v76
	v_exp_f32_e32 v77, v77
	v_mul_f32_e32 v79, 0xbfb8aa3b, v71
	v_exp_f32_e32 v78, v78
	v_exp_f32_e32 v79, v79
	v_add_f32_e32 v76, 1.0, v76
	v_add_f32_e32 v77, 1.0, v77
	v_rcp_f32_e32 v76, v76
	v_rcp_f32_e32 v77, v77
	v_add_f32_e32 v78, 1.0, v78
	v_add_f32_e32 v79, 1.0, v79
	v_rcp_f32_e32 v78, v78
	v_rcp_f32_e32 v79, v79
	v_pk_mul_f32 v[68:69], v[68:69], v[76:77]
	v_cvt_pk_bf16_f32 v72, v72, v73
	v_pk_mul_f32 v[64:65], v[64:65], v[68:69]
	v_pk_mul_f32 v[68:69], v[70:71], v[78:79]
	v_cvt_pk_bf16_f32 v64, v64, v65
	v_pk_mul_f32 v[66:67], v[66:67], v[68:69]
	v_cvt_pk_bf16_f32 v73, v74, v75
	v_cvt_pk_bf16_f32 v65, v66, v67
	v_mul_f32_e32 v66, 0xbfb8aa3b, v60
	v_mul_f32_e32 v67, 0xbfb8aa3b, v61
	v_mad_i64_i32 v[74:75], s[48:49], v84, s66, v[120:121]
	v_exp_f32_e32 v66, v66
	v_exp_f32_e32 v67, v67
	v_lshl_add_u64 v[74:75], v[74:75], 0, s[56:57]
	v_lshl_add_u64 v[74:75], v[74:75], 0, s[10:11]
	v_lshl_add_u64 v[74:75], v[74:75], 0, v[138:139]
	global_store_dwordx2 v[74:75], v[64:65], off offset:128
	v_add_f32_e32 v64, 1.0, v66
	v_add_f32_e32 v65, 1.0, v67
	v_mul_f32_e32 v66, 0xbfb8aa3b, v62
	v_mul_f32_e32 v67, 0xbfb8aa3b, v63
	v_exp_f32_e32 v66, v66
	v_exp_f32_e32 v67, v67
	v_rcp_f32_e32 v64, v64
	v_rcp_f32_e32 v65, v65
	v_add_f32_e32 v66, 1.0, v66
	v_add_f32_e32 v67, 1.0, v67
	v_rcp_f32_e32 v66, v66
	v_rcp_f32_e32 v67, v67
	v_pk_mul_f32 v[60:61], v[60:61], v[64:65]
	v_add_u32_e32 v68, 0x80, v152
	v_pk_mul_f32 v[56:57], v[56:57], v[60:61]
	v_pk_mul_f32 v[60:61], v[62:63], v[66:67]
	v_mul_f32_e32 v62, 0xbfb8aa3b, v54
	v_pk_mul_f32 v[58:59], v[58:59], v[60:61]
	v_mul_f32_e32 v60, 0xbfb8aa3b, v52
	v_mul_f32_e32 v61, 0xbfb8aa3b, v53
	v_exp_f32_e32 v60, v60
	v_exp_f32_e32 v61, v61
	v_mul_f32_e32 v63, 0xbfb8aa3b, v55
	v_exp_f32_e32 v62, v62
	v_exp_f32_e32 v63, v63
	v_add_f32_e32 v60, 1.0, v60
	v_add_f32_e32 v61, 1.0, v61
	v_rcp_f32_e32 v60, v60
	v_rcp_f32_e32 v61, v61
	v_add_f32_e32 v62, 1.0, v62
	v_add_f32_e32 v63, 1.0, v63
	v_rcp_f32_e32 v62, v62
	v_rcp_f32_e32 v63, v63
	v_pk_mul_f32 v[52:53], v[52:53], v[60:61]
	v_cvt_pk_bf16_f32 v56, v56, v57
	v_pk_mul_f32 v[48:49], v[48:49], v[52:53]
	v_pk_mul_f32 v[52:53], v[54:55], v[62:63]
	v_cvt_pk_bf16_f32 v48, v48, v49
	v_pk_mul_f32 v[50:51], v[50:51], v[52:53]
	v_cvt_pk_bf16_f32 v57, v58, v59
	v_cvt_pk_bf16_f32 v49, v50, v51
	v_mul_f32_e32 v50, 0xbfb8aa3b, v44
	v_mul_f32_e32 v51, 0xbfb8aa3b, v45
	v_mad_i64_i32 v[58:59], s[48:49], v68, s66, v[120:121]
	v_exp_f32_e32 v50, v50
	v_exp_f32_e32 v51, v51
	v_lshl_add_u64 v[58:59], v[58:59], 0, s[56:57]
	v_lshl_add_u64 v[58:59], v[58:59], 0, s[10:11]
	v_lshl_add_u64 v[58:59], v[58:59], 0, v[138:139]
	global_store_dwordx2 v[58:59], v[48:49], off offset:128
	v_add_f32_e32 v48, 1.0, v50
	v_add_f32_e32 v49, 1.0, v51
	v_mul_f32_e32 v50, 0xbfb8aa3b, v46
	v_mul_f32_e32 v51, 0xbfb8aa3b, v47
	v_exp_f32_e32 v50, v50
	v_exp_f32_e32 v51, v51
	v_rcp_f32_e32 v48, v48
	v_rcp_f32_e32 v49, v49
	v_add_f32_e32 v50, 1.0, v50
	v_add_f32_e32 v51, 1.0, v51
	v_rcp_f32_e32 v50, v50
	v_rcp_f32_e32 v51, v51
	v_pk_mul_f32 v[44:45], v[44:45], v[48:49]
	v_add_u32_e32 v52, 0x90, v152
	v_pk_mul_f32 v[40:41], v[40:41], v[44:45]
	v_pk_mul_f32 v[44:45], v[46:47], v[50:51]
	v_mul_f32_e32 v46, 0xbfb8aa3b, v38
	v_pk_mul_f32 v[42:43], v[42:43], v[44:45]
	v_mul_f32_e32 v44, 0xbfb8aa3b, v36
	v_mul_f32_e32 v45, 0xbfb8aa3b, v37
	v_exp_f32_e32 v44, v44
	v_exp_f32_e32 v45, v45
	v_mul_f32_e32 v47, 0xbfb8aa3b, v39
	v_exp_f32_e32 v46, v46
	v_exp_f32_e32 v47, v47
	v_add_f32_e32 v44, 1.0, v44
	v_add_f32_e32 v45, 1.0, v45
	v_rcp_f32_e32 v44, v44
	v_rcp_f32_e32 v45, v45
	v_add_f32_e32 v46, 1.0, v46
	v_add_f32_e32 v47, 1.0, v47
	v_rcp_f32_e32 v46, v46
	v_rcp_f32_e32 v47, v47
	v_pk_mul_f32 v[36:37], v[36:37], v[44:45]
	v_cvt_pk_bf16_f32 v40, v40, v41
	v_pk_mul_f32 v[32:33], v[32:33], v[36:37]
	v_pk_mul_f32 v[36:37], v[38:39], v[46:47]
	v_cvt_pk_bf16_f32 v32, v32, v33
	v_pk_mul_f32 v[34:35], v[34:35], v[36:37]
	v_cvt_pk_bf16_f32 v41, v42, v43
	v_cvt_pk_bf16_f32 v33, v34, v35
	v_mul_f32_e32 v34, 0xbfb8aa3b, v28
	v_mul_f32_e32 v35, 0xbfb8aa3b, v29
	v_mad_i64_i32 v[42:43], s[48:49], v52, s66, v[120:121]
	v_exp_f32_e32 v34, v34
	v_exp_f32_e32 v35, v35
	v_lshl_add_u64 v[42:43], v[42:43], 0, s[56:57]
	v_lshl_add_u64 v[42:43], v[42:43], 0, s[10:11]
	v_lshl_add_u64 v[42:43], v[42:43], 0, v[138:139]
	global_store_dwordx2 v[42:43], v[32:33], off offset:128
	v_add_f32_e32 v32, 1.0, v34
	v_add_f32_e32 v33, 1.0, v35
	v_mul_f32_e32 v34, 0xbfb8aa3b, v30
	v_mul_f32_e32 v35, 0xbfb8aa3b, v31
	v_exp_f32_e32 v34, v34
	v_exp_f32_e32 v35, v35
	v_rcp_f32_e32 v32, v32
	v_rcp_f32_e32 v33, v33
	v_add_f32_e32 v34, 1.0, v34
	v_add_f32_e32 v35, 1.0, v35
	v_rcp_f32_e32 v34, v34
	v_rcp_f32_e32 v35, v35
	v_pk_mul_f32 v[28:29], v[28:29], v[32:33]
	v_add_u32_e32 v36, 0xa0, v152
	v_pk_mul_f32 v[24:25], v[24:25], v[28:29]
	v_pk_mul_f32 v[28:29], v[30:31], v[34:35]
	v_mul_f32_e32 v30, 0xbfb8aa3b, v22
	v_pk_mul_f32 v[26:27], v[26:27], v[28:29]
	v_mul_f32_e32 v28, 0xbfb8aa3b, v20
	v_mul_f32_e32 v29, 0xbfb8aa3b, v21
	v_exp_f32_e32 v28, v28
	v_exp_f32_e32 v29, v29
	v_mul_f32_e32 v31, 0xbfb8aa3b, v23
	v_exp_f32_e32 v30, v30
	v_exp_f32_e32 v31, v31
	v_add_f32_e32 v28, 1.0, v28
	v_add_f32_e32 v29, 1.0, v29
	v_rcp_f32_e32 v28, v28
	v_rcp_f32_e32 v29, v29
	v_add_f32_e32 v30, 1.0, v30
	v_add_f32_e32 v31, 1.0, v31
	v_rcp_f32_e32 v30, v30
	v_rcp_f32_e32 v31, v31
	v_pk_mul_f32 v[20:21], v[20:21], v[28:29]
	v_cvt_pk_bf16_f32 v24, v24, v25
	v_pk_mul_f32 v[16:17], v[16:17], v[20:21]
	v_pk_mul_f32 v[20:21], v[22:23], v[30:31]
	v_cvt_pk_bf16_f32 v16, v16, v17
	v_pk_mul_f32 v[18:19], v[18:19], v[20:21]
	v_cvt_pk_bf16_f32 v25, v26, v27
	v_cvt_pk_bf16_f32 v17, v18, v19
	v_mul_f32_e32 v18, 0xbfb8aa3b, v12
	v_mul_f32_e32 v19, 0xbfb8aa3b, v13
	v_mad_i64_i32 v[26:27], s[48:49], v36, s66, v[120:121]
	v_exp_f32_e32 v18, v18
	v_exp_f32_e32 v19, v19
	v_lshl_add_u64 v[26:27], v[26:27], 0, s[56:57]
	v_lshl_add_u64 v[26:27], v[26:27], 0, s[10:11]
	v_lshl_add_u64 v[26:27], v[26:27], 0, v[138:139]
	global_store_dwordx2 v[26:27], v[16:17], off offset:128
	v_add_f32_e32 v16, 1.0, v18
	v_add_f32_e32 v17, 1.0, v19
	v_mul_f32_e32 v18, 0xbfb8aa3b, v14
	v_mul_f32_e32 v19, 0xbfb8aa3b, v15
	v_exp_f32_e32 v18, v18
	v_exp_f32_e32 v19, v19
	v_rcp_f32_e32 v16, v16
	v_rcp_f32_e32 v17, v17
	v_add_f32_e32 v18, 1.0, v18
	v_add_f32_e32 v19, 1.0, v19
	v_rcp_f32_e32 v18, v18
	v_rcp_f32_e32 v19, v19
	v_pk_mul_f32 v[12:13], v[12:13], v[16:17]
	v_add_u32_e32 v20, 0xb0, v152
	v_pk_mul_f32 v[8:9], v[8:9], v[12:13]
	v_pk_mul_f32 v[12:13], v[14:15], v[18:19]
	v_mul_f32_e32 v14, 0xbfb8aa3b, v6
	v_pk_mul_f32 v[10:11], v[10:11], v[12:13]
	v_mul_f32_e32 v12, 0xbfb8aa3b, v4
	v_mul_f32_e32 v13, 0xbfb8aa3b, v5
	v_exp_f32_e32 v12, v12
	v_exp_f32_e32 v13, v13
	v_mul_f32_e32 v15, 0xbfb8aa3b, v7
	v_exp_f32_e32 v14, v14
	v_exp_f32_e32 v15, v15
	v_add_f32_e32 v12, 1.0, v12
	v_add_f32_e32 v13, 1.0, v13
	v_rcp_f32_e32 v12, v12
	v_rcp_f32_e32 v13, v13
	v_add_f32_e32 v14, 1.0, v14
	v_add_f32_e32 v15, 1.0, v15
	v_rcp_f32_e32 v14, v14
	v_rcp_f32_e32 v15, v15
	v_cvt_pk_bf16_f32 v8, v8, v9
	v_cvt_pk_bf16_f32 v9, v10, v11
	v_mad_i64_i32 v[10:11], s[48:49], v20, s66, v[120:121]
	v_pk_mul_f32 v[4:5], v[4:5], v[12:13]
	v_lshl_add_u64 v[10:11], v[10:11], 0, s[56:57]
	v_pk_mul_f32 v[0:1], v[0:1], v[4:5]
	v_pk_mul_f32 v[4:5], v[6:7], v[14:15]
	v_lshl_add_u64 v[10:11], v[10:11], 0, s[10:11]
	v_pk_mul_f32 v[2:3], v[2:3], v[4:5]
	v_lshl_add_u64 v[10:11], v[10:11], 0, v[138:139]
	v_cvt_pk_bf16_f32 v0, v0, v1
	v_cvt_pk_bf16_f32 v1, v2, v3
	s_waitcnt vmcnt(5)
	buffer_store_dwordx4 v[166:169], v246, s[76:79], s5 offen nt
	buffer_store_dwordx4 v[170:173], v246, s[76:79], s5 offen offset:1024 nt
	buffer_store_dwordx4 v[174:177], v246, s[76:79], s5 offen offset:2048 nt
	buffer_store_dwordx4 v[178:181], v246, s[76:79], s5 offen offset:3072 nt
	buffer_store_dwordx4 v[182:185], v238, s[76:79], s5 offen nt
	buffer_store_dwordx4 v[186:189], v238, s[76:79], s5 offen offset:1024 nt
	buffer_store_dwordx4 v[190:193], v238, s[76:79], s5 offen offset:2048 nt
	buffer_store_dwordx4 v[194:197], v238, s[76:79], s5 offen offset:3072 nt
	buffer_store_dwordx4 v[198:201], v239, s[76:79], s5 offen nt
	buffer_store_dwordx4 v[202:205], v239, s[76:79], s5 offen offset:1024 nt
	buffer_store_dwordx4 v[206:209], v239, s[76:79], s5 offen offset:2048 nt
	buffer_store_dwordx4 v[210:213], v239, s[76:79], s5 offen offset:3072 nt
	buffer_store_dwordx4 v[158:161], v246, s[76:79], vcc_lo offen nt
	buffer_store_dwordx4 v[214:217], v246, s[76:79], vcc_lo offen offset:1024 nt
	buffer_store_dwordx4 v[218:221], v246, s[76:79], vcc_lo offen offset:2048 nt
	buffer_store_dwordx4 v[222:225], v246, s[76:79], vcc_lo offen offset:3072 nt
	buffer_store_dwordx4 v[226:229], v238, s[76:79], vcc_lo offen nt
	buffer_store_dwordx4 v[230:233], v238, s[76:79], vcc_lo offen offset:1024 nt
	buffer_store_dwordx4 v[234:237], v238, s[76:79], vcc_lo offen offset:2048 nt
	buffer_store_dwordx4 v[242:245], v238, s[76:79], vcc_lo offen offset:3072 nt
	buffer_store_dwordx4 v[112:115], v239, s[76:79], vcc_lo offen nt
	buffer_store_dwordx4 v[108:111], v239, s[76:79], vcc_lo offen offset:1024 nt
	buffer_store_dwordx4 v[116:119], v239, s[76:79], vcc_lo offen offset:2048 nt
	buffer_store_dwordx4 v[96:99], v239, s[76:79], vcc_lo offen offset:3072 nt
	s_add_u32 s5, s5, 0x30000
	s_cmp_ge_u32 s5, 0x120000
	s_cselect_b32 s5, 0x70000000, s5
	s_andn2_b64 vcc, exec, s[6:7]
	s_mov_b64 s[6:7], -1
	global_store_dwordx2 v[122:123], v[124:125], off
	global_store_dwordx2 v[106:107], v[104:105], off
	global_store_dwordx2 v[90:91], v[88:89], off
	global_store_dwordx2 v[74:75], v[72:73], off
	global_store_dwordx2 v[58:59], v[56:57], off
	global_store_dwordx2 v[42:43], v[40:41], off
	global_store_dwordx2 v[26:27], v[24:25], off
	global_store_dwordx2 v[10:11], v[8:9], off
	global_store_dwordx2 v[10:11], v[0:1], off offset:128
	s_cbranch_vccnz .LBB0_1654
	s_andn2_b64 vcc, exec, s[22:23]
	s_cbranch_vccnz .LBB0_1653
	s_barrier
	s_branch .LBB0_1653
